# stack15 + hipcc's vmcnt(0) in front of the MA K-loop executed only on the phase's first unit
# speedup vs baseline: 1.0001x; 1.0001x over previous
; #define PG8_STAGE(bufoff, gbase, voff) do { _Pragma("unroll") for (int _i = 0; _i < 2; ++_i) \
;         __builtin_amdgcn_global_load_lds((const unsigned*)((const char*)(gbase) + (voff)[_i]), (PG8_LAS unsigned*)(lds + (bufoff) + ldsw + _i * 8192), 16, 0, 0); } while (0)
; #define PG8_LDA(dst, b, h) do { _Pragma("unroll") for (int m = 0; m < 4; ++m) _Pragma("unroll") for (int k = 0; k < 2; ++k) dst[m][k] = *(const PG8_LAS bf16x8*)(lds + PG8_SA(b, h) + aoff + m * 2048 + k * 1024); } while (0)
; #define PG8_WAIT_V(n) asm volatile("s_waitcnt vmcnt(" #n ")" ::: "memory")
;     __device__ __forceinline__ void operator()(const f32x4 (&acc)[2][2][4][2], const Unit& u, int wr, int wc, int fr_, int fq) const {
;     ...
;         f32x4 bv[2][2];
; #pragma unroll
;         for (int bj = 0; bj < 2; ++bj)
; #pragma unroll
;             for (int n = 0; n < 2; ++n) bv[bj][n] = *(const f32x4*)(bmg + (gate ? colt : 0) + cl + bj * HALF + 4 * n) * (gate ? 1.0f : 0.0f);
; template <class Epi, class Sched, bool ALIGN_EPI = false, bool SP2 = false, bool ABLK = false, bool BBLK = false>
; __device__ __forceinline__ void gemm_phase(PG8_LAS unsigned char* lds, const Gemm g, const Sched& S, const Epi& E) {
;     ...
;         const bool has_next = S.next(ui + 1, nxt);
;         const char* nA = has_next ? (const char*)g.A + (size_t)nxt.pm * tstepA : cA; const char* nB = has_next ? (const char*)g.Bt + (size_t)nxt.pn * tstepB : cB;
;         for (int t = 0; t < nt; t += 2) {
;             const bool last = (t == nt - 2);
;             const char* a1 = cA + (size_t)(t + 1) * kstepA;
;             const char* a2 = last ? nA : cA + (size_t)(t + 2) * kstepA; const char* b2 = last ? nB : cB + (size_t)(t + 2) * kstepB;
;             const char* a3 = a2 + kstepA; const char* b3 = b2 + kstepB;
;             if (last && has_next) S.a_ready(nxt);
;             if constexpr (SP2) {
;             PG8_LDB(B0, 0, 0); PG8_LDB(B1, 0, 1); PG8_SCHED; PG8_LDA(At, 0, 0); PG8_STAGE(PG8_SA(1, 1), a1 + hstepA, voffA);
;             PG8_WAIT_V(8); PG8_WAIT_L(0); PG8_BAR; PG8_MMA(0, 0, At, B0); PG8_MMA(0, 1, At, B1); PG8_BAR; PG8_SCHED;
;             PG8_LDA(At, 0, 1); PG8_STAGE(PG8_SB(0, 0), b2, voffB); PG8_STAGE(PG8_SB(0, 1), b2 + hstepB, voffB); PG8_STAGE(PG8_SA(0, 0), a2, voffA);
;             PG8_WAIT_V(8); PG8_WAIT_L(0); PG8_BAR; PG8_MMA(1, 0, At, B0); PG8_MMA(1, 1, At, B1); PG8_BAR; PG8_SCHED;
.Lw0_594:
	s_lshl_b32 s100, s8, 8
	s_add_i32 s100, s100, 0xfffff200
	s_cmp_gt_i32 s8, 13
	s_cselect_b32 s100, s100, 0
	s_ashr_i32 s101, s100, 31
	v_lshl_add_u64 v[250:251], s[100:101], 2, v[154:155]
	global_load_dwordx4 v[224:227], v[250:251], off
	global_load_dwordx4 v[246:249], v[250:251], off offset:16
	global_load_dwordx4 v[188:191], v[250:251], off offset:528
	s_nop 0
	global_load_dwordx4 v[250:253], v[250:251], off offset:512
	s_add_u32 s30, s0, 0x4000
	s_addc_u32 s31, s1, 0
	s_cmp_eq_u32 s41, 28
	s_cselect_b32 s36, s16, s30
	s_cselect_b32 s37, s9, s31
	s_cselect_b32 s34, s23, s29
	s_cselect_b32 s35, s21, s40
	s_add_u32 s30, s36, 0x8000
	s_addc_u32 s31, s37, 0
	s_add_i32 s60, 0, 0x10000
	s_add_i32 s75, 0, 0x14000
	v_add_u32_e32 v142, s60, v169
	v_add_u32_e32 v171, s75, v169
	ds_read_b128 v[130:133], v142
	ds_read_b128 v[134:137], v142 offset:1024
	ds_read_b128 v[138:141], v142 offset:2048
	ds_read_b128 v[142:145], v142 offset:3072
	ds_read_b128 v[160:163], v171
	ds_read_b128 v[164:167], v171 offset:1024
	ds_read_b128 v[172:175], v171 offset:2048
	ds_read_b128 v[176:179], v171 offset:3072
	v_lshl_add_u64 v[184:185], s[0:1], 0, v[156:157]
	s_add_i32 m0, s83, 0xc000
	ds_read_b128 v[180:183], v170
	ds_read_b128 v[196:199], v170 offset:1024
	ds_read_b128 v[200:203], v170 offset:2048
	ds_read_b128 v[204:207], v170 offset:3072
	ds_read_b128 v[208:211], v170 offset:4096
	ds_read_b128 v[212:215], v170 offset:5120
	ds_read_b128 v[216:219], v170 offset:6144
	ds_read_b128 v[220:223], v170 offset:7168
	global_load_lds_dwordx4 v[184:185], off
	v_lshl_add_u64 v[184:185], s[0:1], 0, v[158:159]
	s_add_i32 m0, s83, 0xe000
	s_nop 0
	global_load_lds_dwordx4 v[184:185], off
	s_waitcnt vmcnt(8)
	s_waitcnt lgkmcnt(0)
	s_barrier
	s_setprio 1
	s_waitcnt lgkmcnt(0)
	v_mfma_f32_16x16x32_bf16 v[126:129], v[130:133], v[180:183], 0
	v_mfma_f32_16x16x32_bf16 v[122:125], v[138:141], v[180:183], 0
	v_mfma_f32_16x16x32_bf16 v[110:113], v[130:133], v[200:203], 0
	v_mfma_f32_16x16x32_bf16 v[106:109], v[138:141], v[200:203], 0
	v_mfma_f32_16x16x32_bf16 v[94:97], v[130:133], v[208:211], 0
	v_mfma_f32_16x16x32_bf16 v[90:93], v[138:141], v[208:211], 0
	v_mfma_f32_16x16x32_bf16 v[78:81], v[130:133], v[216:219], 0
	v_mfma_f32_16x16x32_bf16 v[74:77], v[138:141], v[216:219], 0
	v_mfma_f32_16x16x32_bf16 v[126:129], v[134:137], v[196:199], v[126:129]
	v_mfma_f32_16x16x32_bf16 v[122:125], v[142:145], v[196:199], v[122:125]
	v_mfma_f32_16x16x32_bf16 v[110:113], v[134:137], v[204:207], v[110:113]
	v_mfma_f32_16x16x32_bf16 v[106:109], v[142:145], v[204:207], v[106:109]
	v_mfma_f32_16x16x32_bf16 v[94:97], v[134:137], v[212:215], v[94:97]
	v_mfma_f32_16x16x32_bf16 v[90:93], v[142:145], v[212:215], v[90:93]
	v_mfma_f32_16x16x32_bf16 v[78:81], v[134:137], v[220:223], v[78:81]
	v_mfma_f32_16x16x32_bf16 v[74:77], v[142:145], v[220:223], v[74:77]
	s_setprio 0
	s_setprio 1
	v_mfma_f32_16x16x32_bf16 v[118:121], v[160:163], v[180:183], 0
	v_mfma_f32_16x16x32_bf16 v[114:117], v[172:175], v[180:183], 0
	v_mfma_f32_16x16x32_bf16 v[102:105], v[160:163], v[200:203], 0
	v_mfma_f32_16x16x32_bf16 v[98:101], v[172:175], v[200:203], 0
	v_mfma_f32_16x16x32_bf16 v[86:89], v[160:163], v[208:211], 0
	v_mfma_f32_16x16x32_bf16 v[82:85], v[172:175], v[208:211], 0
	v_mfma_f32_16x16x32_bf16 v[70:73], v[160:163], v[216:219], 0
	v_mfma_f32_16x16x32_bf16 v[66:69], v[172:175], v[216:219], 0
	v_mfma_f32_16x16x32_bf16 v[118:121], v[164:167], v[196:199], v[118:121]
	v_mfma_f32_16x16x32_bf16 v[114:117], v[176:179], v[196:199], v[114:117]
	v_mfma_f32_16x16x32_bf16 v[102:105], v[164:167], v[204:207], v[102:105]
	v_mfma_f32_16x16x32_bf16 v[98:101], v[176:179], v[204:207], v[98:101]
	v_mfma_f32_16x16x32_bf16 v[86:89], v[164:167], v[212:215], v[86:89]
	v_mfma_f32_16x16x32_bf16 v[82:85], v[176:179], v[212:215], v[82:85]
	v_mfma_f32_16x16x32_bf16 v[70:73], v[164:167], v[220:223], v[70:73]
	v_mfma_f32_16x16x32_bf16 v[66:69], v[176:179], v[220:223], v[66:69]
	s_setprio 0
	s_barrier
; #define PG8_STAGE(bufoff, gbase, voff) do { _Pragma("unroll") for (int _i = 0; _i < 2; ++_i) \
;         __builtin_amdgcn_global_load_lds((const unsigned*)((const char*)(gbase) + (voff)[_i]), (PG8_LAS unsigned*)(lds + (bufoff) + ldsw + _i * 8192), 16, 0, 0); } while (0)
; #define PG8_LDA(dst, b, h) do { _Pragma("unroll") for (int m = 0; m < 4; ++m) _Pragma("unroll") for (int k = 0; k < 2; ++k) dst[m][k] = *(const PG8_LAS bf16x8*)(lds + PG8_SA(b, h) + aoff + m * 2048 + k * 1024); } while (0)
; #define PG8_MMA(ai, bj, At, Bt) do { __builtin_amdgcn_s_setprio(1); _Pragma("unroll") for (int m = 0; m < 4; ++m) _Pragma("unroll") for (int n = 0; n < 2; ++n) _Pragma("unroll") for (int k = 0; k < 2; ++k) \
;         acc[ai][bj][m][n] = __builtin_amdgcn_mfma_f32_16x16x32_bf16(Bt[n][k], At[m][k], acc[ai][bj][m][n], 0, 0, 0); __builtin_amdgcn_s_setprio(0); } while (0)
; #define PG8_WAIT_V(n) asm volatile("s_waitcnt vmcnt(" #n ")" ::: "memory")
; #define PG8_WAIT_L(n) asm volatile("s_waitcnt lgkmcnt(" #n ")" ::: "memory")
; #define PG8_BAR __builtin_amdgcn_s_barrier()
; #define PG8_SCHED __builtin_amdgcn_sched_barrier(0)
; template <class Epi, class Sched, bool ALIGN_EPI = false, bool SP2 = false, bool ABLK = false, bool BBLK = false>
; __device__ __forceinline__ void gemm_phase(PG8_LAS unsigned char* lds, const Gemm g, const Sched& S, const Epi& E) {
;     ...
;             PG8_LDA(At, 0, 1); PG8_STAGE(PG8_SB(0, 0), b2, voffB); PG8_STAGE(PG8_SB(0, 1), b2 + hstepB, voffB); PG8_STAGE(PG8_SA(0, 0), a2, voffA);
;             PG8_WAIT_V(8); PG8_WAIT_L(0); PG8_BAR; PG8_MMA(1, 0, At, B0); PG8_MMA(1, 1, At, B1); PG8_BAR; PG8_SCHED;
	s_add_i32 s60, s60, s81
	v_lshl_add_u64 v[184:185], s[34:35], 0, v[148:149]
	s_mov_b32 m0, s60
	ds_read_b128 v[180:183], v170 offset:16384
	ds_read_b128 v[196:199], v170 offset:17408
	ds_read_b128 v[200:203], v170 offset:18432
	ds_read_b128 v[204:207], v170 offset:19456
	ds_read_b128 v[208:211], v170 offset:20480
	ds_read_b128 v[212:215], v170 offset:21504
	ds_read_b128 v[216:219], v170 offset:22528
	ds_read_b128 v[220:223], v170 offset:23552
	global_load_lds_dwordx4 v[184:185], off
	s_add_i32 m0, s60, 0x2000
	s_add_u32 s60, s34, 0x4000
	v_lshl_add_u64 v[184:185], s[34:35], 0, v[152:153]
	s_addc_u32 s61, s35, 0
	s_add_i32 s75, s75, s81
	global_load_lds_dwordx4 v[184:185], off
	v_lshl_add_u64 v[184:185], s[60:61], 0, v[148:149]
	s_mov_b32 m0, s75
	s_nop 0
	global_load_lds_dwordx4 v[184:185], off
	v_lshl_add_u64 v[184:185], s[60:61], 0, v[152:153]
	s_add_i32 m0, s75, 0x2000
	s_nop 0
	global_load_lds_dwordx4 v[184:185], off
	v_lshl_add_u64 v[184:185], s[36:37], 0, v[146:147]
	s_mov_b32 m0, s83
	s_nop 0
	global_load_lds_dwordx4 v[184:185], off
	v_lshl_add_u64 v[184:185], s[36:37], 0, v[150:151]
	s_mov_b32 m0, s84
	s_nop 0
	global_load_lds_dwordx4 v[184:185], off
	s_waitcnt vmcnt(8)
	s_waitcnt lgkmcnt(0)
	s_barrier
	s_setprio 1
	s_waitcnt lgkmcnt(0)
	v_mfma_f32_16x16x32_bf16 v[62:65], v[130:133], v[180:183], 0
	v_mfma_f32_16x16x32_bf16 v[58:61], v[138:141], v[180:183], 0
	v_mfma_f32_16x16x32_bf16 v[46:49], v[130:133], v[200:203], 0
	v_mfma_f32_16x16x32_bf16 v[42:45], v[138:141], v[200:203], 0
	v_mfma_f32_16x16x32_bf16 v[30:33], v[130:133], v[208:211], 0
	v_mfma_f32_16x16x32_bf16 v[26:29], v[138:141], v[208:211], 0
	v_mfma_f32_16x16x32_bf16 v[14:17], v[130:133], v[216:219], 0
	v_mfma_f32_16x16x32_bf16 v[10:13], v[138:141], v[216:219], 0
	v_mfma_f32_16x16x32_bf16 v[62:65], v[134:137], v[196:199], v[62:65]
	v_mfma_f32_16x16x32_bf16 v[58:61], v[142:145], v[196:199], v[58:61]
	v_mfma_f32_16x16x32_bf16 v[46:49], v[134:137], v[204:207], v[46:49]
	v_mfma_f32_16x16x32_bf16 v[42:45], v[142:145], v[204:207], v[42:45]
	v_mfma_f32_16x16x32_bf16 v[30:33], v[134:137], v[212:215], v[30:33]
	v_mfma_f32_16x16x32_bf16 v[26:29], v[142:145], v[212:215], v[26:29]
	v_mfma_f32_16x16x32_bf16 v[14:17], v[134:137], v[220:223], v[14:17]
	v_mfma_f32_16x16x32_bf16 v[10:13], v[142:145], v[220:223], v[10:13]
	s_setprio 0
	s_setprio 1
	v_mfma_f32_16x16x32_bf16 v[54:57], v[160:163], v[180:183], 0
	v_mfma_f32_16x16x32_bf16 v[50:53], v[172:175], v[180:183], 0
	v_mfma_f32_16x16x32_bf16 v[38:41], v[160:163], v[200:203], 0
	v_mfma_f32_16x16x32_bf16 v[34:37], v[172:175], v[200:203], 0
	v_mfma_f32_16x16x32_bf16 v[22:25], v[160:163], v[208:211], 0
	v_mfma_f32_16x16x32_bf16 v[18:21], v[172:175], v[208:211], 0
	v_mfma_f32_16x16x32_bf16 v[6:9], v[160:163], v[216:219], 0
	v_mfma_f32_16x16x32_bf16 v[2:5], v[172:175], v[216:219], 0
	v_mfma_f32_16x16x32_bf16 v[54:57], v[164:167], v[196:199], v[54:57]
	v_mfma_f32_16x16x32_bf16 v[50:53], v[176:179], v[196:199], v[50:53]
	v_mfma_f32_16x16x32_bf16 v[38:41], v[164:167], v[204:207], v[38:41]
	v_mfma_f32_16x16x32_bf16 v[34:37], v[176:179], v[204:207], v[34:37]
	v_mfma_f32_16x16x32_bf16 v[22:25], v[164:167], v[212:215], v[22:25]
	v_mfma_f32_16x16x32_bf16 v[18:21], v[176:179], v[212:215], v[18:21]
	v_mfma_f32_16x16x32_bf16 v[6:9], v[164:167], v[220:223], v[6:9]
	v_mfma_f32_16x16x32_bf16 v[2:5], v[176:179], v[220:223], v[2:5]
	s_setprio 0
	s_barrier
	s_branch .Lmid_594
